# G1: odd workgroup groups walk their unit table backwards (different epilogue types at the same time inside an XCD); v75 otherwise
# speedup vs baseline: 1.0046x; 1.0046x over previous
.LBB0_201:
	s_cmp_gt_i32 s39, 0
	s_cselect_b64 s[18:19], -1, 0
	s_cmp_lt_i32 s39, 1
	s_cbranch_scc1 .LBB0_204
	s_add_i32 s4, 0, 0x20200
	s_bitcmp1_b32 s2, 3
	s_cbranch_scc0 .Lrev0_skip
	s_add_i32 s99, s39, -1
	s_lshl_b32 s99, s99, 4
	s_add_i32 s4, s4, s99
.Lrev0_skip:
	v_mov_b32_e32 v0, s4
	ds_read_b96 v[0:2], v0
	s_waitcnt lgkmcnt(0)
	v_readfirstlane_b32 s4, v2
	s_cmp_eq_u32 s4, 0
	v_readfirstlane_b32 s14, v0
	v_readfirstlane_b32 s16, v1
	s_cselect_b64 s[4:5], -1, 0
	s_andn2_b64 vcc, exec, s[18:19]
	s_cbranch_vccz .LBB0_205

.LBB0_210:
	s_add_i32 s44, s80, 1
	s_cmp_lt_i32 s44, s39
	s_cselect_b64 s[74:75], -1, 0
	s_cmp_ge_i32 s44, s39
	s_cbranch_scc1 .LBB0_212
	s_mov_b32 s15, s44
	s_bitcmp1_b32 s2, 3
	s_cbranch_scc0 .Lrev1_skip
	s_sub_i32 s15, s39, s44
	s_add_i32 s15, s15, -1
.Lrev1_skip:
	s_lshl_b32 s15, s15, 4
	s_add_i32 s15, s15, 0
	s_add_i32 s15, s15, 0x20200
	v_mov_b32_e32 v0, s15
	ds_read_b96 v[0:2], v0
	s_waitcnt lgkmcnt(0)
	v_readfirstlane_b32 s64, v0
	v_readfirstlane_b32 s66, v1
	v_readfirstlane_b32 s29, v2
